# P4 Q/K epilogue: row-scale loads issued together at branch start (per-group waits kept)
# baseline (speedup 1.0000x reference)
.LBB0_356:
.LBB0_357:
	s_lshl_b32 s23, s34, 8
	s_add_i32 s23, s23, s88
	v_or_b32_e32 v158, s23, v139
	s_lshl_b32 s3, s30, 8
	v_or_b32_e32 v156, 16, v158
	v_or_b32_e32 v154, 32, v158
	v_or_b32_e32 v152, 48, v158
	s_cmp_lt_i32 s30, 8
	s_mov_b64 s[0:1], -1
	v_ashrrev_i32_e32 v159, 31, v158
	v_ashrrev_i32_e32 v157, 31, v156
	v_ashrrev_i32_e32 v155, 31, v154
	v_ashrrev_i32_e32 v153, 31, v152
	s_cbranch_scc1 .LBB0_359
	v_lshl_add_u64 v[162:163], v[158:159], 2, s[12:13]
	global_load_dword v238, v[162:163], off
	global_load_dword v239, v[162:163], off offset:64
	global_load_dword v240, v[162:163], off offset:128
	global_load_dword v241, v[162:163], off offset:192
	global_load_dword v242, v[162:163], off offset:512
	global_load_dword v243, v[162:163], off offset:576
	global_load_dword v244, v[162:163], off offset:640
	global_load_dword v245, v[162:163], off offset:704
	s_nop 0
	s_add_i32 s0, s45, s3
	s_ashr_i32 s6, s23, 11
	s_ashr_i32 s7, s0, 6
	s_mul_i32 s6, s6, 20
	s_add_i32 s0, s6, s7
	s_ashr_i32 s1, s0, 31
	s_lshl_b64 s[0:1], s[0:1], 18
	s_add_u32 s0, s52, s0
	s_addc_u32 s1, s53, s1
	s_lshr_b32 s23, s23, 2
	s_and_b32 s23, s23, 0x1f0
	v_or_b32_e32 v136, s23, v192
	v_lshlrev_b32_e32 v136, 9, v136
	v_lshl_add_u64 v[168:169], s[0:1], 0, v[136:137]
	v_lshlrev_b32_e32 v160, 1, v138
	v_mov_b32_e32 v161, v137
	v_lshl_add_u64 v[170:171], v[168:169], 0, v[160:161]
	s_waitcnt vmcnt(0)
	v_fmamk_f32 v149, v238, 0x3a000000, v198
	v_cmp_gt_f32_e32 vcc, s60, v149
	v_mul_f32_e32 v164, 0x4b800000, v149
	s_nop 0
	v_cndmask_b32_e32 v149, v149, v164, vcc
	v_rsq_f32_e32 v149, v149
	s_nop 0
	v_mul_f32_e32 v164, 0x45800000, v149
	v_cndmask_b32_e32 v164, v149, v164, vcc
	v_pk_mul_f32 v[166:167], v[126:127], v[164:165] op_sel_hi:[1,0]
	v_pk_mul_f32 v[172:173], v[124:125], v[164:165] op_sel_hi:[1,0]
	v_pk_mul_f32 v[174:175], v[122:123], v[164:165] op_sel_hi:[1,0]
	v_pk_mul_f32 v[176:177], v[120:121], v[164:165] op_sel_hi:[1,0]
	v_cvt_pk_bf16_f32 v164, v172, v173
	v_cvt_pk_bf16_f32 v165, v166, v167
	v_lshlrev_b32_e32 v149, 4, v156
	v_cvt_pk_bf16_f32 v166, v176, v177
	v_cvt_pk_bf16_f32 v167, v174, v175
	global_store_dwordx4 v[170:171], v[164:167], off
	s_nop 1
	v_lshl_add_u64 v[166:167], v[156:157], 2, s[12:13]
	v_and_b32_e32 v164, 0x1f0, v149
	s_nop 0
	v_mov_b32_e32 v165, v137
	v_lshl_add_u64 v[168:169], v[168:169], 0, v[164:165]
	s_waitcnt vmcnt(0)
	v_fmamk_f32 v149, v239, 0x3a000000, v198
	v_cmp_gt_f32_e32 vcc, s60, v149
	v_mul_f32_e32 v170, 0x4b800000, v149
	s_nop 0
	v_cndmask_b32_e32 v149, v149, v170, vcc
	v_rsq_f32_e32 v149, v149
	s_nop 0
	v_mul_f32_e32 v170, 0x45800000, v149
	v_cndmask_b32_e32 v170, v149, v170, vcc
	v_lshrrev_b32_e32 v149, 2, v154
	v_pk_mul_f32 v[172:173], v[110:111], v[170:171] op_sel_hi:[1,0]
	v_and_or_b32 v149, v149, s62, v193
	v_pk_mul_f32 v[174:175], v[108:109], v[170:171] op_sel_hi:[1,0]
	v_pk_mul_f32 v[176:177], v[106:107], v[170:171] op_sel_hi:[1,0]
	v_pk_mul_f32 v[178:179], v[104:105], v[170:171] op_sel_hi:[1,0]
	v_cvt_pk_bf16_f32 v170, v174, v175
	v_cvt_pk_bf16_f32 v171, v172, v173
	s_nop 0
	v_cvt_pk_bf16_f32 v172, v178, v179
	v_cvt_pk_bf16_f32 v173, v176, v177
	global_store_dwordx4 v[168:169], v[170:173], off
	v_lshlrev_b32_e32 v168, 9, v149
	v_mov_b32_e32 v169, v137
	v_lshl_add_u64 v[170:171], s[0:1], 0, v[168:169]
	v_lshl_add_u64 v[176:177], v[170:171], 0, v[160:161]
	v_lshl_add_u64 v[170:171], v[154:155], 2, s[12:13]
	s_nop 0
	s_waitcnt vmcnt(0)
	v_fmamk_f32 v149, v240, 0x3a000000, v198
	v_cmp_gt_f32_e32 vcc, s60, v149
	v_mul_f32_e32 v172, 0x4b800000, v149
	s_nop 0
	v_cndmask_b32_e32 v149, v149, v172, vcc
	v_rsq_f32_e32 v149, v149
	s_nop 0
	v_mul_f32_e32 v172, 0x45800000, v149
	v_cndmask_b32_e32 v172, v149, v172, vcc
	v_lshrrev_b32_e32 v149, 2, v152
	v_pk_mul_f32 v[174:175], v[94:95], v[172:173] op_sel_hi:[1,0]
	v_pk_mul_f32 v[178:179], v[92:93], v[172:173] op_sel_hi:[1,0]
	v_pk_mul_f32 v[180:181], v[90:91], v[172:173] op_sel_hi:[1,0]
	v_pk_mul_f32 v[182:183], v[88:89], v[172:173] op_sel_hi:[1,0]
	v_cvt_pk_bf16_f32 v172, v178, v179
	v_cvt_pk_bf16_f32 v173, v174, v175
	v_and_or_b32 v149, v149, s62, v193
	v_cvt_pk_bf16_f32 v174, v182, v183
	v_cvt_pk_bf16_f32 v175, v180, v181
	global_store_dwordx4 v[176:177], v[172:175], off
	s_nop 1
	v_lshlrev_b32_e32 v172, 9, v149
	v_mov_b32_e32 v173, v137
	v_lshlrev_b32_e32 v149, 4, v152
	v_lshl_add_u64 v[176:177], s[0:1], 0, v[172:173]
	v_and_b32_e32 v174, 0x1f0, v149
	v_mov_b32_e32 v175, v137
	v_lshl_add_u64 v[178:179], v[176:177], 0, v[174:175]
	v_lshl_add_u64 v[176:177], v[152:153], 2, s[12:13]
	s_nop 0
	s_add_i32 s0, s50, s3
	s_waitcnt vmcnt(0)
	v_fmamk_f32 v149, v241, 0x3a000000, v198
	v_cmp_gt_f32_e32 vcc, s60, v149
	v_mul_f32_e32 v180, 0x4b800000, v149
	s_nop 0
	v_cndmask_b32_e32 v149, v149, v180, vcc
	v_rsq_f32_e32 v149, v149
	s_nop 0
	v_mul_f32_e32 v180, 0x45800000, v149
	v_cndmask_b32_e32 v180, v149, v180, vcc
	v_pk_mul_f32 v[182:183], v[78:79], v[180:181] op_sel_hi:[1,0]
	v_pk_mul_f32 v[184:185], v[76:77], v[180:181] op_sel_hi:[1,0]
	v_pk_mul_f32 v[186:187], v[74:75], v[180:181] op_sel_hi:[1,0]
	v_pk_mul_f32 v[188:189], v[72:73], v[180:181] op_sel_hi:[1,0]
	v_cvt_pk_bf16_f32 v180, v184, v185
	v_cvt_pk_bf16_f32 v181, v182, v183
	s_nop 0
	v_cvt_pk_bf16_f32 v182, v188, v189
	v_cvt_pk_bf16_f32 v183, v186, v187
	global_store_dwordx4 v[178:179], v[180:183], off
	s_nop 1
	v_add_u32_e32 v180, 0x80, v158
	v_ashrrev_i32_e32 v149, 11, v180
	v_mad_i32_i24 v178, v149, 20, s7
	v_ashrrev_i32_e32 v179, 31, v178
	v_lshlrev_b64 v[178:179], 18, v[178:179]
	v_lshl_add_u64 v[188:189], s[52:53], 0, v[178:179]
	v_lshrrev_b32_e32 v178, 2, v180
	v_and_or_b32 v178, v178, s61, v192
	v_lshlrev_b32_e32 v178, 9, v178
	v_mov_b32_e32 v179, v137
	v_lshl_add_u64 v[180:181], v[188:189], 0, v[178:179]
	v_lshl_add_u64 v[184:185], v[180:181], 0, v[160:161]
	s_nop 0
	s_ashr_i32 s7, s0, 6
	s_add_i32 s0, s6, s7
	s_ashr_i32 s1, s0, 31
	s_lshl_b64 s[0:1], s[0:1], 18
	s_add_u32 s0, s52, s0
	s_addc_u32 s1, s53, s1
	s_waitcnt vmcnt(0)
	v_fmamk_f32 v180, v242, 0x3a000000, v198
	v_cmp_gt_f32_e32 vcc, s60, v180
	v_mul_f32_e32 v181, 0x4b800000, v180
	s_nop 0
	v_cndmask_b32_e32 v180, v180, v181, vcc
	v_rsq_f32_e32 v180, v180
	s_nop 0
	v_mul_f32_e32 v181, 0x45800000, v180
	v_cndmask_b32_e32 v180, v180, v181, vcc
	v_pk_mul_f32 v[182:183], v[62:63], v[180:181] op_sel_hi:[1,0]
	v_pk_mul_f32 v[186:187], v[60:61], v[180:181] op_sel_hi:[1,0]
	v_pk_mul_f32 v[200:201], v[58:59], v[180:181] op_sel_hi:[1,0]
	v_pk_mul_f32 v[202:203], v[56:57], v[180:181] op_sel_hi:[1,0]
	v_cvt_pk_bf16_f32 v180, v186, v187
	v_cvt_pk_bf16_f32 v181, v182, v183
	s_nop 0
	v_cvt_pk_bf16_f32 v182, v202, v203
	v_cvt_pk_bf16_f32 v183, v200, v201
	global_store_dwordx4 v[184:185], v[180:183], off
	s_nop 1
	v_add_u32_e32 v182, 0x90, v158
	v_lshrrev_b32_e32 v180, 2, v182
	v_and_or_b32 v180, v180, s61, v192
	v_lshlrev_b32_e32 v180, 9, v180
	v_mov_b32_e32 v181, v137
	v_lshlrev_b32_e32 v182, 4, v182
	v_lshl_add_u64 v[184:185], v[188:189], 0, v[180:181]
	v_and_b32_e32 v182, 0x1f0, v182
	v_mov_b32_e32 v183, v137
	v_lshl_add_u64 v[200:201], v[184:185], 0, v[182:183]
	s_nop 0
	s_waitcnt vmcnt(0)
	v_fmamk_f32 v184, v243, 0x3a000000, v198
	v_cmp_gt_f32_e32 vcc, s60, v184
	v_mul_f32_e32 v185, 0x4b800000, v184
	s_nop 0
	v_cndmask_b32_e32 v184, v184, v185, vcc
	v_rsq_f32_e32 v184, v184
	s_nop 0
	v_mul_f32_e32 v185, 0x45800000, v184
	v_cndmask_b32_e32 v184, v184, v185, vcc
	v_pk_mul_f32 v[186:187], v[46:47], v[184:185] op_sel_hi:[1,0]
	v_pk_mul_f32 v[202:203], v[44:45], v[184:185] op_sel_hi:[1,0]
	v_pk_mul_f32 v[204:205], v[42:43], v[184:185] op_sel_hi:[1,0]
	v_pk_mul_f32 v[206:207], v[40:41], v[184:185] op_sel_hi:[1,0]
	v_cvt_pk_bf16_f32 v184, v202, v203
	v_cvt_pk_bf16_f32 v185, v186, v187
	s_nop 0
	v_cvt_pk_bf16_f32 v186, v206, v207
	v_cvt_pk_bf16_f32 v187, v204, v205
	global_store_dwordx4 v[200:201], v[184:187], off
	s_nop 0
	s_waitcnt vmcnt(0)
	v_fmamk_f32 v196, v244, 0x3a000000, v198
	v_cmp_gt_f32_e32 vcc, s60, v196
	v_mul_f32_e32 v199, 0x4b800000, v196
	v_add_u32_e32 v184, 0xa0, v158
	v_cndmask_b32_e32 v196, v196, v199, vcc
	v_rsq_f32_e32 v196, v196
	v_lshrrev_b32_e32 v184, 2, v184
	v_and_or_b32 v184, v184, s62, v192
	v_lshlrev_b32_e32 v184, 9, v184
	v_mov_b32_e32 v185, v137
	v_mul_f32_e32 v199, 0x45800000, v196
	v_lshl_add_u64 v[186:187], v[188:189], 0, v[184:185]
	v_cndmask_b32_e32 v200, v196, v199, vcc
	v_lshl_add_u64 v[186:187], v[186:187], 0, v[160:161]
	v_pk_mul_f32 v[202:203], v[30:31], v[200:201] op_sel_hi:[1,0]
	v_add_u32_e32 v196, 0xb0, v158
	v_pk_mul_f32 v[204:205], v[28:29], v[200:201] op_sel_hi:[1,0]
	v_pk_mul_f32 v[206:207], v[26:27], v[200:201] op_sel_hi:[1,0]
	v_pk_mul_f32 v[208:209], v[24:25], v[200:201] op_sel_hi:[1,0]
	v_cvt_pk_bf16_f32 v200, v204, v205
	v_cvt_pk_bf16_f32 v201, v202, v203
	s_nop 0
	v_cvt_pk_bf16_f32 v202, v208, v209
	v_cvt_pk_bf16_f32 v203, v206, v207
	global_store_dwordx4 v[186:187], v[200:203], off
	v_lshrrev_b32_e32 v186, 2, v196
	v_and_or_b32 v186, v186, s62, v192
	v_lshlrev_b32_e32 v186, 9, v186
	v_mov_b32_e32 v187, v137
	v_lshl_add_u64 v[200:201], v[188:189], 0, v[186:187]
	v_lshlrev_b32_e32 v188, 4, v196
	s_nop 0
	v_and_b32_e32 v188, 0x1f0, v188
	v_mov_b32_e32 v189, v137
	v_lshl_add_u64 v[204:205], v[200:201], 0, v[188:189]
	s_waitcnt vmcnt(0)
	v_fmamk_f32 v196, v245, 0x3a000000, v198
	v_cmp_gt_f32_e32 vcc, s60, v196
	v_mul_f32_e32 v199, 0x4b800000, v196
	s_nop 0
	v_cndmask_b32_e32 v196, v196, v199, vcc
	v_rsq_f32_e32 v196, v196
	s_nop 0
	v_mul_f32_e32 v199, 0x45800000, v196
	v_cndmask_b32_e32 v200, v196, v199, vcc
	v_pk_mul_f32 v[202:203], v[14:15], v[200:201] op_sel_hi:[1,0]
	v_pk_mul_f32 v[206:207], v[12:13], v[200:201] op_sel_hi:[1,0]
	v_pk_mul_f32 v[208:209], v[10:11], v[200:201] op_sel_hi:[1,0]
	v_pk_mul_f32 v[210:211], v[8:9], v[200:201] op_sel_hi:[1,0]
	v_cvt_pk_bf16_f32 v200, v206, v207
	v_cvt_pk_bf16_f32 v201, v202, v203
	s_nop 0
	v_cvt_pk_bf16_f32 v202, v210, v211
	v_cvt_pk_bf16_f32 v203, v208, v209
	global_store_dwordx4 v[204:205], v[200:203], off
	v_lshl_add_u64 v[204:205], s[0:1], 0, v[136:137]
	s_nop 0
	v_lshl_add_u64 v[206:207], v[204:205], 0, v[160:161]
	s_waitcnt vmcnt(0)
	v_fmamk_f32 v136, v238, 0x3a000000, v198
	v_cmp_gt_f32_e32 vcc, s60, v136
	v_mul_f32_e32 v196, 0x4b800000, v136
	s_nop 0
	v_cndmask_b32_e32 v136, v136, v196, vcc
	v_rsq_f32_e32 v136, v136
	s_nop 0
	v_mul_f32_e32 v196, 0x45800000, v136
	v_cndmask_b32_e32 v136, v136, v196, vcc
	v_pk_mul_f32 v[202:203], v[118:119], v[136:137] op_sel_hi:[1,0]
	v_pk_mul_f32 v[200:201], v[116:117], v[136:137] op_sel_hi:[1,0]
	v_pk_mul_f32 v[208:209], v[114:115], v[136:137] op_sel_hi:[1,0]
	v_pk_mul_f32 v[210:211], v[112:113], v[136:137] op_sel_hi:[1,0]
	v_cvt_pk_bf16_f32 v200, v200, v201
	v_cvt_pk_bf16_f32 v201, v202, v203
	s_nop 0
	v_cvt_pk_bf16_f32 v202, v210, v211
	v_cvt_pk_bf16_f32 v203, v208, v209
	global_store_dwordx4 v[206:207], v[200:203], off
	s_nop 0
	s_waitcnt vmcnt(0)
	v_fmamk_f32 v136, v239, 0x3a000000, v198
	v_lshl_add_u64 v[200:201], v[204:205], 0, v[164:165]
	v_cmp_gt_f32_e32 vcc, s60, v136
	v_mul_f32_e32 v164, 0x4b800000, v136
	s_nop 0
	v_cndmask_b32_e32 v136, v136, v164, vcc
	v_rsq_f32_e32 v136, v136
	s_nop 0
	v_mul_f32_e32 v164, 0x45800000, v136
	v_cndmask_b32_e32 v136, v136, v164, vcc
	v_pk_mul_f32 v[166:167], v[102:103], v[136:137] op_sel_hi:[1,0]
	v_pk_mul_f32 v[164:165], v[100:101], v[136:137] op_sel_hi:[1,0]
	v_pk_mul_f32 v[202:203], v[98:99], v[136:137] op_sel_hi:[1,0]
	v_pk_mul_f32 v[204:205], v[96:97], v[136:137] op_sel_hi:[1,0]
	v_cvt_pk_bf16_f32 v164, v164, v165
	v_cvt_pk_bf16_f32 v165, v166, v167
	s_nop 0
	v_cvt_pk_bf16_f32 v166, v204, v205
	v_cvt_pk_bf16_f32 v167, v202, v203
	global_store_dwordx4 v[200:201], v[164:167], off
	s_nop 0
	s_waitcnt vmcnt(0)
	v_fmamk_f32 v136, v240, 0x3a000000, v198
	v_lshl_add_u64 v[164:165], s[0:1], 0, v[168:169]
	v_lshl_add_u64 v[168:169], v[164:165], 0, v[160:161]
	v_cmp_gt_f32_e32 vcc, s60, v136
	v_mul_f32_e32 v164, 0x4b800000, v136
	s_nop 0
	v_cndmask_b32_e32 v136, v136, v164, vcc
	v_rsq_f32_e32 v136, v136
	s_nop 0
	v_mul_f32_e32 v164, 0x45800000, v136
	v_cndmask_b32_e32 v136, v136, v164, vcc
	v_pk_mul_f32 v[166:167], v[86:87], v[136:137] op_sel_hi:[1,0]
	v_pk_mul_f32 v[164:165], v[84:85], v[136:137] op_sel_hi:[1,0]
	v_pk_mul_f32 v[170:171], v[82:83], v[136:137] op_sel_hi:[1,0]
	v_pk_mul_f32 v[200:201], v[80:81], v[136:137] op_sel_hi:[1,0]
	v_cvt_pk_bf16_f32 v164, v164, v165
	v_cvt_pk_bf16_f32 v165, v166, v167
	s_nop 0
	v_cvt_pk_bf16_f32 v166, v200, v201
	v_cvt_pk_bf16_f32 v167, v170, v171
	global_store_dwordx4 v[168:169], v[164:167], off
	s_nop 0
	s_waitcnt vmcnt(0)
	v_fmamk_f32 v136, v241, 0x3a000000, v198
	v_lshl_add_u64 v[164:165], s[0:1], 0, v[172:173]
	v_lshl_add_u64 v[168:169], v[164:165], 0, v[174:175]
	v_cmp_gt_f32_e32 vcc, s60, v136
	v_mul_f32_e32 v164, 0x4b800000, v136
	s_mov_b64 s[0:1], 0
	v_cndmask_b32_e32 v136, v136, v164, vcc
	v_rsq_f32_e32 v136, v136
	s_nop 0
	v_mul_f32_e32 v164, 0x45800000, v136
	v_cndmask_b32_e32 v136, v136, v164, vcc
	v_pk_mul_f32 v[166:167], v[70:71], v[136:137] op_sel_hi:[1,0]
	v_pk_mul_f32 v[164:165], v[68:69], v[136:137] op_sel_hi:[1,0]
	v_pk_mul_f32 v[170:171], v[66:67], v[136:137] op_sel_hi:[1,0]
	v_pk_mul_f32 v[172:173], v[64:65], v[136:137] op_sel_hi:[1,0]
	v_cvt_pk_bf16_f32 v164, v164, v165
	v_cvt_pk_bf16_f32 v165, v166, v167
	s_nop 0
	v_cvt_pk_bf16_f32 v166, v172, v173
	v_cvt_pk_bf16_f32 v167, v170, v171
	global_store_dwordx4 v[168:169], v[164:167], off
	s_nop 0
	s_waitcnt vmcnt(0)
	v_fmamk_f32 v136, v242, 0x3a000000, v198
	v_mad_i32_i24 v164, v149, 20, s7
	v_cmp_gt_f32_e32 vcc, s60, v136
	v_mul_f32_e32 v149, 0x4b800000, v136
	v_ashrrev_i32_e32 v165, 31, v164
	v_cndmask_b32_e32 v136, v136, v149, vcc
	v_rsq_f32_e32 v136, v136
	v_lshlrev_b64 v[164:165], 18, v[164:165]
	v_lshl_add_u64 v[168:169], s[52:53], 0, v[164:165]
	v_lshl_add_u64 v[164:165], v[168:169], 0, v[178:179]
	v_mul_f32_e32 v149, 0x45800000, v136
	v_cndmask_b32_e32 v136, v136, v149, vcc
	v_lshl_add_u64 v[170:171], v[164:165], 0, v[160:161]
	v_pk_mul_f32 v[166:167], v[54:55], v[136:137] op_sel_hi:[1,0]
	v_pk_mul_f32 v[164:165], v[52:53], v[136:137] op_sel_hi:[1,0]
	v_pk_mul_f32 v[172:173], v[50:51], v[136:137] op_sel_hi:[1,0]
	v_pk_mul_f32 v[174:175], v[48:49], v[136:137] op_sel_hi:[1,0]
	v_cvt_pk_bf16_f32 v164, v164, v165
	v_cvt_pk_bf16_f32 v165, v166, v167
	s_nop 0
	v_cvt_pk_bf16_f32 v166, v174, v175
	v_cvt_pk_bf16_f32 v167, v172, v173
	global_store_dwordx4 v[170:171], v[164:167], off
	s_nop 0
	s_waitcnt vmcnt(0)
	v_fmamk_f32 v136, v243, 0x3a000000, v198
	v_cmp_gt_f32_e32 vcc, s60, v136
	v_mul_f32_e32 v149, 0x4b800000, v136
	v_lshl_add_u64 v[164:165], v[168:169], 0, v[180:181]
	v_cndmask_b32_e32 v136, v136, v149, vcc
	v_rsq_f32_e32 v136, v136
	v_lshl_add_u64 v[170:171], v[164:165], 0, v[182:183]
	v_mul_f32_e32 v149, 0x45800000, v136
	v_cndmask_b32_e32 v136, v136, v149, vcc
	v_pk_mul_f32 v[166:167], v[38:39], v[136:137] op_sel_hi:[1,0]
	v_pk_mul_f32 v[164:165], v[36:37], v[136:137] op_sel_hi:[1,0]
	v_pk_mul_f32 v[172:173], v[34:35], v[136:137] op_sel_hi:[1,0]
	v_pk_mul_f32 v[174:175], v[32:33], v[136:137] op_sel_hi:[1,0]
	v_cvt_pk_bf16_f32 v164, v164, v165
	v_cvt_pk_bf16_f32 v165, v166, v167
	s_nop 0
	v_cvt_pk_bf16_f32 v166, v174, v175
	v_cvt_pk_bf16_f32 v167, v172, v173
	global_store_dwordx4 v[170:171], v[164:167], off
	s_nop 0
	s_waitcnt vmcnt(0)
	v_fmamk_f32 v136, v244, 0x3a000000, v198
	v_cmp_gt_f32_e32 vcc, s60, v136
	v_mul_f32_e32 v149, 0x4b800000, v136
	v_lshl_add_u64 v[164:165], v[168:169], 0, v[184:185]
	v_cndmask_b32_e32 v136, v136, v149, vcc
	v_rsq_f32_e32 v136, v136
	v_lshl_add_u64 v[160:161], v[164:165], 0, v[160:161]
	v_mul_f32_e32 v149, 0x45800000, v136
	v_cndmask_b32_e32 v136, v136, v149, vcc
	v_pk_mul_f32 v[166:167], v[22:23], v[136:137] op_sel_hi:[1,0]
	v_pk_mul_f32 v[164:165], v[20:21], v[136:137] op_sel_hi:[1,0]
	v_pk_mul_f32 v[170:171], v[18:19], v[136:137] op_sel_hi:[1,0]
	v_pk_mul_f32 v[172:173], v[16:17], v[136:137] op_sel_hi:[1,0]
	v_cvt_pk_bf16_f32 v164, v164, v165
	v_cvt_pk_bf16_f32 v165, v166, v167
	s_nop 0
	v_cvt_pk_bf16_f32 v166, v172, v173
	v_cvt_pk_bf16_f32 v167, v170, v171
	global_store_dwordx4 v[160:161], v[164:167], off
	s_nop 0
	v_lshl_add_u64 v[160:161], v[168:169], 0, v[186:187]
	v_lshl_add_u64 v[164:165], v[160:161], 0, v[188:189]
	s_waitcnt vmcnt(0)
	v_fmamk_f32 v136, v245, 0x3a000000, v198
	v_cmp_gt_f32_e32 vcc, s60, v136
	v_mul_f32_e32 v149, 0x4b800000, v136
	s_nop 0
	v_cndmask_b32_e32 v136, v136, v149, vcc
	v_rsq_f32_e32 v136, v136
	s_nop 0
	v_mul_f32_e32 v149, 0x45800000, v136
	v_cndmask_b32_e32 v136, v136, v149, vcc
	v_pk_mul_f32 v[162:163], v[6:7], v[136:137] op_sel_hi:[1,0]
	v_pk_mul_f32 v[160:161], v[4:5], v[136:137] op_sel_hi:[1,0]
	v_pk_mul_f32 v[166:167], v[2:3], v[136:137] op_sel_hi:[1,0]
	v_pk_mul_f32 v[168:169], v[0:1], v[136:137] op_sel_hi:[1,0]
	v_cvt_pk_bf16_f32 v160, v160, v161
	v_cvt_pk_bf16_f32 v161, v162, v163
	s_nop 0
	v_cvt_pk_bf16_f32 v162, v168, v169
	v_cvt_pk_bf16_f32 v163, v166, v167
	global_store_dwordx4 v[164:165], v[160:163], off
.LBB0_359:
	s_andn2_b64 vcc, exec, s[0:1]
	s_cbranch_vccnz .LBB0_361
	v_lshl_add_u64 v[160:161], v[158:159], 2, s[12:13]
	global_load_dword v238, v[160:161], off
	global_load_dword v239, v[160:161], off offset:64
	global_load_dword v240, v[160:161], off offset:128
	global_load_dword v241, v[160:161], off offset:192
	global_load_dword v242, v[160:161], off offset:512
	global_load_dword v243, v[160:161], off offset:576
	global_load_dword v244, v[160:161], off offset:640
	global_load_dword v245, v[160:161], off offset:704
	s_nop 0
	v_or_b32_e32 v162, s3, v191
	v_lshlrev_b64 v[158:159], 12, v[158:159]
	v_ashrrev_i32_e32 v163, 31, v162
	v_lshl_add_u64 v[158:159], s[48:49], 0, v[158:159]
	v_lshlrev_b64 v[162:163], 1, v[162:163]
	v_lshl_add_u64 v[158:159], v[158:159], 0, v[162:163]
	v_lshl_add_u64 v[164:165], v[156:157], 2, s[12:13]
	s_mov_b32 s3, 0x80000
	s_mov_b64 s[0:1], 0x80000
	s_waitcnt vmcnt(0)
	v_fmamk_f32 v136, v238, 0x3a000000, v198
	v_mul_f32_e32 v149, 0x4b800000, v136
	v_cmp_gt_f32_e32 vcc, s60, v136
	s_nop 1
	v_cndmask_b32_e32 v136, v136, v149, vcc
	v_rsq_f32_e32 v136, v136
	s_nop 0
	v_mul_f32_e32 v149, 0x45800000, v136
	v_cndmask_b32_e32 v136, v136, v149, vcc
	v_mul_f32_e32 v136, 0x3e38aa3b, v136
	v_pk_mul_f32 v[126:127], v[126:127], v[136:137] op_sel_hi:[1,0]
	v_pk_mul_f32 v[124:125], v[124:125], v[136:137] op_sel_hi:[1,0]
	v_pk_mul_f32 v[122:123], v[122:123], v[136:137] op_sel_hi:[1,0]
	v_pk_mul_f32 v[120:121], v[120:121], v[136:137] op_sel_hi:[1,0]
	v_pk_mul_f32 v[166:167], v[114:115], v[136:137] op_sel_hi:[1,0]
	v_pk_mul_f32 v[168:169], v[112:113], v[136:137] op_sel_hi:[1,0]
	v_cvt_pk_bf16_f32 v112, v124, v125
	v_cvt_pk_bf16_f32 v113, v126, v127
	v_cvt_pk_bf16_f32 v114, v120, v121
	v_cvt_pk_bf16_f32 v115, v122, v123
	v_pk_mul_f32 v[118:119], v[118:119], v[136:137] op_sel_hi:[1,0]
	v_pk_mul_f32 v[116:117], v[116:117], v[136:137] op_sel_hi:[1,0]
	global_store_dwordx4 v[158:159], v[112:115], off
	s_nop 1
	v_cvt_pk_bf16_f32 v112, v116, v117
	v_cvt_pk_bf16_f32 v113, v118, v119
	v_cvt_pk_bf16_f32 v114, v168, v169
	v_cvt_pk_bf16_f32 v115, v166, v167
	global_store_dwordx4 v[158:159], v[112:115], off offset:256
	s_nop 0
	s_nop 0
	v_lshlrev_b64 v[112:113], 12, v[156:157]
	v_lshl_add_u64 v[112:113], s[48:49], 0, v[112:113]
	v_lshl_add_u64 v[112:113], v[112:113], 0, v[162:163]
	s_waitcnt vmcnt(0)
	v_fmamk_f32 v114, v239, 0x3a000000, v198
	v_mul_f32_e32 v115, 0x4b800000, v114
	v_cmp_gt_f32_e32 vcc, s60, v114
	s_nop 1
	v_cndmask_b32_e32 v114, v114, v115, vcc
	v_rsq_f32_e32 v116, v114
	v_lshl_add_u64 v[114:115], v[154:155], 2, s[12:13]
	v_mul_f32_e32 v117, 0x45800000, v116
	v_cndmask_b32_e32 v116, v116, v117, vcc
	v_mul_f32_e32 v116, 0x3e38aa3b, v116
	v_pk_mul_f32 v[110:111], v[110:111], v[116:117] op_sel_hi:[1,0]
	v_pk_mul_f32 v[108:109], v[108:109], v[116:117] op_sel_hi:[1,0]
	v_pk_mul_f32 v[106:107], v[106:107], v[116:117] op_sel_hi:[1,0]
	v_pk_mul_f32 v[104:105], v[104:105], v[116:117] op_sel_hi:[1,0]
	v_pk_mul_f32 v[102:103], v[102:103], v[116:117] op_sel_hi:[1,0]
	v_pk_mul_f32 v[100:101], v[100:101], v[116:117] op_sel_hi:[1,0]
	v_pk_mul_f32 v[118:119], v[98:99], v[116:117] op_sel_hi:[1,0]
	v_pk_mul_f32 v[116:117], v[96:97], v[116:117] op_sel_hi:[1,0]
	v_cvt_pk_bf16_f32 v96, v108, v109
	v_cvt_pk_bf16_f32 v97, v110, v111
	v_cvt_pk_bf16_f32 v98, v104, v105
	v_cvt_pk_bf16_f32 v99, v106, v107
	global_store_dwordx4 v[112:113], v[96:99], off
	s_nop 1
	v_cvt_pk_bf16_f32 v96, v100, v101
	v_cvt_pk_bf16_f32 v97, v102, v103
	v_cvt_pk_bf16_f32 v98, v116, v117
	v_cvt_pk_bf16_f32 v99, v118, v119
	global_store_dwordx4 v[112:113], v[96:99], off offset:256
	s_nop 0
	s_nop 0
	v_lshlrev_b64 v[96:97], 12, v[154:155]
	v_lshl_add_u64 v[96:97], s[48:49], 0, v[96:97]
	v_lshl_add_u64 v[96:97], v[96:97], 0, v[162:163]
	s_waitcnt vmcnt(0)
	v_fmamk_f32 v98, v240, 0x3a000000, v198
	v_mul_f32_e32 v99, 0x4b800000, v98
	v_cmp_gt_f32_e32 vcc, s60, v98
	s_nop 1
	v_cndmask_b32_e32 v98, v98, v99, vcc
	v_rsq_f32_e32 v100, v98
	v_lshl_add_u64 v[98:99], v[152:153], 2, s[12:13]
	v_mul_f32_e32 v101, 0x45800000, v100
	v_cndmask_b32_e32 v100, v100, v101, vcc
	v_mul_f32_e32 v100, 0x3e38aa3b, v100
	v_pk_mul_f32 v[94:95], v[94:95], v[100:101] op_sel_hi:[1,0]
	v_pk_mul_f32 v[92:93], v[92:93], v[100:101] op_sel_hi:[1,0]
	v_pk_mul_f32 v[90:91], v[90:91], v[100:101] op_sel_hi:[1,0]
	v_pk_mul_f32 v[88:89], v[88:89], v[100:101] op_sel_hi:[1,0]
	v_pk_mul_f32 v[86:87], v[86:87], v[100:101] op_sel_hi:[1,0]
	v_pk_mul_f32 v[84:85], v[84:85], v[100:101] op_sel_hi:[1,0]
	v_pk_mul_f32 v[102:103], v[82:83], v[100:101] op_sel_hi:[1,0]
	v_pk_mul_f32 v[100:101], v[80:81], v[100:101] op_sel_hi:[1,0]
	v_cvt_pk_bf16_f32 v80, v92, v93
	v_cvt_pk_bf16_f32 v81, v94, v95
	v_cvt_pk_bf16_f32 v82, v88, v89
	v_cvt_pk_bf16_f32 v83, v90, v91
	global_store_dwordx4 v[96:97], v[80:83], off
	s_nop 1
	v_cvt_pk_bf16_f32 v80, v84, v85
	v_cvt_pk_bf16_f32 v81, v86, v87
	v_cvt_pk_bf16_f32 v82, v100, v101
	v_cvt_pk_bf16_f32 v83, v102, v103
	global_store_dwordx4 v[96:97], v[80:83], off offset:256
	s_nop 0
	s_waitcnt vmcnt(0)
	v_fmamk_f32 v80, v241, 0x3a000000, v198
	v_mul_f32_e32 v81, 0x4b800000, v80
	v_cmp_gt_f32_e32 vcc, s60, v80
	s_nop 1
	v_cndmask_b32_e32 v80, v80, v81, vcc
	v_rsq_f32_e32 v82, v80
	v_lshlrev_b64 v[80:81], 12, v[152:153]
	v_lshl_add_u64 v[80:81], s[48:49], 0, v[80:81]
	v_lshl_add_u64 v[80:81], v[80:81], 0, v[162:163]
	v_mul_f32_e32 v83, 0x45800000, v82
	v_cndmask_b32_e32 v82, v82, v83, vcc
	v_mul_f32_e32 v82, 0x3e38aa3b, v82
	v_pk_mul_f32 v[78:79], v[78:79], v[82:83] op_sel_hi:[1,0]
	v_pk_mul_f32 v[76:77], v[76:77], v[82:83] op_sel_hi:[1,0]
	v_pk_mul_f32 v[74:75], v[74:75], v[82:83] op_sel_hi:[1,0]
	v_pk_mul_f32 v[72:73], v[72:73], v[82:83] op_sel_hi:[1,0]
	v_pk_mul_f32 v[70:71], v[70:71], v[82:83] op_sel_hi:[1,0]
	v_pk_mul_f32 v[68:69], v[68:69], v[82:83] op_sel_hi:[1,0]
	v_pk_mul_f32 v[84:85], v[66:67], v[82:83] op_sel_hi:[1,0]
	v_pk_mul_f32 v[82:83], v[64:65], v[82:83] op_sel_hi:[1,0]
	v_cvt_pk_bf16_f32 v64, v76, v77
	v_cvt_pk_bf16_f32 v65, v78, v79
	v_cvt_pk_bf16_f32 v66, v72, v73
	v_cvt_pk_bf16_f32 v67, v74, v75
	global_store_dwordx4 v[80:81], v[64:67], off
	s_nop 1
	v_cvt_pk_bf16_f32 v64, v68, v69
	v_cvt_pk_bf16_f32 v65, v70, v71
	v_cvt_pk_bf16_f32 v66, v82, v83
	v_cvt_pk_bf16_f32 v67, v84, v85
	global_store_dwordx4 v[80:81], v[64:67], off offset:256
	s_nop 0
	s_nop 0
	v_lshl_add_u64 v[64:65], v[158:159], 0, s[0:1]
	s_mov_b64 s[0:1], 0x90000
	s_waitcnt vmcnt(0)
	v_fmamk_f32 v66, v242, 0x3a000000, v198
	v_mul_f32_e32 v67, 0x4b800000, v66
	v_cmp_gt_f32_e32 vcc, s60, v66
	s_nop 1
	v_cndmask_b32_e32 v66, v66, v67, vcc
	v_rsq_f32_e32 v68, v66
	v_add_co_u32_e64 v66, s[6:7], s3, v158
	s_mov_b32 s3, 0x90000
	v_mul_f32_e32 v69, 0x45800000, v68
	v_cndmask_b32_e32 v68, v68, v69, vcc
	v_mul_f32_e32 v68, 0x3e38aa3b, v68
	v_addc_co_u32_e64 v67, s[6:7], 0, v159, s[6:7]
	v_pk_mul_f32 v[62:63], v[62:63], v[68:69] op_sel_hi:[1,0]
	v_pk_mul_f32 v[60:61], v[60:61], v[68:69] op_sel_hi:[1,0]
	v_pk_mul_f32 v[58:59], v[58:59], v[68:69] op_sel_hi:[1,0]
	v_pk_mul_f32 v[56:57], v[56:57], v[68:69] op_sel_hi:[1,0]
	v_pk_mul_f32 v[54:55], v[54:55], v[68:69] op_sel_hi:[1,0]
	v_pk_mul_f32 v[52:53], v[52:53], v[68:69] op_sel_hi:[1,0]
	v_pk_mul_f32 v[70:71], v[50:51], v[68:69] op_sel_hi:[1,0]
	v_pk_mul_f32 v[68:69], v[48:49], v[68:69] op_sel_hi:[1,0]
	v_cvt_pk_bf16_f32 v48, v60, v61
	v_cvt_pk_bf16_f32 v49, v62, v63
	v_cvt_pk_bf16_f32 v50, v56, v57
	v_cvt_pk_bf16_f32 v51, v58, v59
	global_store_dwordx4 v[66:67], v[48:51], off
	s_nop 1
	v_cvt_pk_bf16_f32 v48, v52, v53
	v_cvt_pk_bf16_f32 v49, v54, v55
	v_cvt_pk_bf16_f32 v50, v68, v69
	v_cvt_pk_bf16_f32 v51, v70, v71
	global_store_dwordx4 v[64:65], v[48:51], off offset:256
	s_nop 0
	s_nop 0
	v_lshl_add_u64 v[48:49], v[158:159], 0, s[0:1]
	s_mov_b64 s[0:1], 0xa0000
	s_waitcnt vmcnt(0)
	v_fmamk_f32 v50, v243, 0x3a000000, v198
	v_mul_f32_e32 v51, 0x4b800000, v50
	v_cmp_gt_f32_e32 vcc, s60, v50
	s_nop 1
	v_cndmask_b32_e32 v50, v50, v51, vcc
	v_rsq_f32_e32 v52, v50
	v_add_co_u32_e64 v50, s[6:7], s3, v158
	s_mov_b32 s3, 0xa0000
	v_mul_f32_e32 v53, 0x45800000, v52
	v_cndmask_b32_e32 v52, v52, v53, vcc
	v_mul_f32_e32 v52, 0x3e38aa3b, v52
	v_addc_co_u32_e64 v51, s[6:7], 0, v159, s[6:7]
	v_pk_mul_f32 v[46:47], v[46:47], v[52:53] op_sel_hi:[1,0]
	v_pk_mul_f32 v[44:45], v[44:45], v[52:53] op_sel_hi:[1,0]
	v_pk_mul_f32 v[42:43], v[42:43], v[52:53] op_sel_hi:[1,0]
	v_pk_mul_f32 v[40:41], v[40:41], v[52:53] op_sel_hi:[1,0]
	v_pk_mul_f32 v[38:39], v[38:39], v[52:53] op_sel_hi:[1,0]
	v_pk_mul_f32 v[36:37], v[36:37], v[52:53] op_sel_hi:[1,0]
	v_pk_mul_f32 v[54:55], v[34:35], v[52:53] op_sel_hi:[1,0]
	v_pk_mul_f32 v[52:53], v[32:33], v[52:53] op_sel_hi:[1,0]
	v_cvt_pk_bf16_f32 v32, v44, v45
	v_cvt_pk_bf16_f32 v33, v46, v47
	v_cvt_pk_bf16_f32 v34, v40, v41
	v_cvt_pk_bf16_f32 v35, v42, v43
	global_store_dwordx4 v[50:51], v[32:35], off
	s_nop 1
	v_cvt_pk_bf16_f32 v32, v36, v37
	v_cvt_pk_bf16_f32 v33, v38, v39
	v_cvt_pk_bf16_f32 v34, v52, v53
	v_cvt_pk_bf16_f32 v35, v54, v55
	global_store_dwordx4 v[48:49], v[32:35], off offset:256
	s_nop 0
	s_nop 0
	v_lshl_add_u64 v[32:33], v[158:159], 0, s[0:1]
	s_mov_b64 s[0:1], 0xb0000
	s_waitcnt vmcnt(0)
	v_fmamk_f32 v34, v244, 0x3a000000, v198
	v_mul_f32_e32 v35, 0x4b800000, v34
	v_cmp_gt_f32_e32 vcc, s60, v34
	s_nop 1
	v_cndmask_b32_e32 v34, v34, v35, vcc
	v_rsq_f32_e32 v36, v34
	v_add_co_u32_e64 v34, s[6:7], s3, v158
	s_mov_b32 s3, 0xb0000
	v_mul_f32_e32 v37, 0x45800000, v36
	v_cndmask_b32_e32 v36, v36, v37, vcc
	v_mul_f32_e32 v36, 0x3e38aa3b, v36
	v_addc_co_u32_e64 v35, s[6:7], 0, v159, s[6:7]
	v_pk_mul_f32 v[30:31], v[30:31], v[36:37] op_sel_hi:[1,0]
	v_pk_mul_f32 v[28:29], v[28:29], v[36:37] op_sel_hi:[1,0]
	v_pk_mul_f32 v[26:27], v[26:27], v[36:37] op_sel_hi:[1,0]
	v_pk_mul_f32 v[24:25], v[24:25], v[36:37] op_sel_hi:[1,0]
	v_pk_mul_f32 v[22:23], v[22:23], v[36:37] op_sel_hi:[1,0]
	v_pk_mul_f32 v[20:21], v[20:21], v[36:37] op_sel_hi:[1,0]
	v_pk_mul_f32 v[38:39], v[18:19], v[36:37] op_sel_hi:[1,0]
	v_pk_mul_f32 v[36:37], v[16:17], v[36:37] op_sel_hi:[1,0]
	v_cvt_pk_bf16_f32 v16, v28, v29
	v_cvt_pk_bf16_f32 v17, v30, v31
	v_cvt_pk_bf16_f32 v18, v24, v25
	v_cvt_pk_bf16_f32 v19, v26, v27
	global_store_dwordx4 v[34:35], v[16:19], off
	s_nop 1
	v_cvt_pk_bf16_f32 v16, v20, v21
	v_cvt_pk_bf16_f32 v17, v22, v23
	v_cvt_pk_bf16_f32 v18, v36, v37
	v_cvt_pk_bf16_f32 v19, v38, v39
	global_store_dwordx4 v[32:33], v[16:19], off offset:256
	s_nop 0
	s_nop 0
	v_lshl_add_u64 v[16:17], v[158:159], 0, s[0:1]
	s_waitcnt vmcnt(0)
	v_fmamk_f32 v18, v245, 0x3a000000, v198
	v_mul_f32_e32 v19, 0x4b800000, v18
	v_cmp_gt_f32_e32 vcc, s60, v18
	s_nop 1
	v_cndmask_b32_e32 v18, v18, v19, vcc
	v_rsq_f32_e32 v20, v18
	v_add_co_u32_e64 v18, s[6:7], s3, v158
	v_mul_f32_e32 v21, 0x45800000, v20
	v_cndmask_b32_e32 v20, v20, v21, vcc
	v_mul_f32_e32 v20, 0x3e38aa3b, v20
	v_addc_co_u32_e64 v19, s[6:7], 0, v159, s[6:7]
	v_pk_mul_f32 v[14:15], v[14:15], v[20:21] op_sel_hi:[1,0]
	v_pk_mul_f32 v[12:13], v[12:13], v[20:21] op_sel_hi:[1,0]
	v_pk_mul_f32 v[10:11], v[10:11], v[20:21] op_sel_hi:[1,0]
	v_pk_mul_f32 v[8:9], v[8:9], v[20:21] op_sel_hi:[1,0]
	v_pk_mul_f32 v[6:7], v[6:7], v[20:21] op_sel_hi:[1,0]
	v_pk_mul_f32 v[4:5], v[4:5], v[20:21] op_sel_hi:[1,0]
	v_pk_mul_f32 v[22:23], v[2:3], v[20:21] op_sel_hi:[1,0]
	v_pk_mul_f32 v[20:21], v[0:1], v[20:21] op_sel_hi:[1,0]
	v_cvt_pk_bf16_f32 v0, v12, v13
	v_cvt_pk_bf16_f32 v1, v14, v15
	v_cvt_pk_bf16_f32 v2, v8, v9
	v_cvt_pk_bf16_f32 v3, v10, v11
	global_store_dwordx4 v[18:19], v[0:3], off
	s_nop 1
	v_cvt_pk_bf16_f32 v0, v4, v5
	v_cvt_pk_bf16_f32 v1, v6, v7
	v_cvt_pk_bf16_f32 v2, v20, v21
	v_cvt_pk_bf16_f32 v3, v22, v23
	global_store_dwordx4 v[16:17], v[0:3], off offset:256
